# pool mixer: 51 x=x+0 no-op adds deleted (exact); on top of attention-loop VALU trims
# speedup vs baseline: 1.0126x; 1.0035x over previous
.LBB0_930:
	s_or_b64 exec, exec, s[2:3]
	v_or_b32_e32 v124, s7, v188
	v_mad_i64_i32 v[132:133], s[2:3], v124, s33, v[190:191]
	v_lshl_add_u64 v[128:129], v[132:133], 0, v[184:185]
	v_lshl_add_u64 v[136:137], v[132:133], 0, v[182:183]
	global_load_dwordx4 v[124:127], v[128:129], off offset:512
	s_nop 0
	global_load_dwordx4 v[128:131], v[128:129], off offset:576
	s_nop 0
	global_load_dwordx4 v[132:135], v[136:137], off offset:512
	s_nop 0
	global_load_dwordx4 v[136:139], v[136:137], off offset:576
	s_cmpk_lt_i32 s6, 0x200
	s_cselect_b32 s2, s89, 0x1000
	s_add_i32 s3, s2, -1
	s_waitcnt lgkmcnt(0)
	s_barrier
	s_and_b32 s3, s3, s8
	v_or_b32_e32 v158, s3, v188
	v_add_u32_e32 v159, v243, v178
	s_and_saveexec_b64 s[6:7], s[36:37]
	s_xor_b64 s[6:7], exec, s[6:7]
	s_cbranch_execz .LBB0_932
	v_add_u32_e32 v148, 2, v158
	v_min_u32_e32 v148, s2, v148
	v_sub_u32_e64 v149, v158, 2 clamp
	v_sub_u32_e32 v148, v148, v149
	v_cvt_f32_i32_e32 v148, v148
	v_div_scale_f32 v149, s[10:11], v148, v148, 1.0
	v_rcp_f32_e32 v150, v149
	s_nop 0
	v_fma_f32 v151, -v149, v150, 1.0
	v_fmac_f32_e32 v150, v151, v150
	v_div_scale_f32 v151, vcc, 1.0, v148, 1.0
	v_mul_f32_e32 v152, v151, v150
	v_fma_f32 v153, -v149, v152, v151
	v_fmac_f32_e32 v152, v153, v150
	v_fma_f32 v149, -v149, v152, v151
	v_div_fmas_f32 v149, v149, v150, v152
	v_div_fixup_f32 v156, v149, v148, 1.0
	ds_read_b128 v[148:151], v159 offset:3296
	ds_read_b128 v[152:155], v159 offset:3824
	ds_read_b128 v[160:163], v159 offset:4352
	ds_read_b128 v[164:167], v159 offset:4880
	s_waitcnt lgkmcnt(0)
	v_lshlrev_b32_e32 v168, 16, v148
	v_and_b32_e32 v169, 0xffff0000, v148
	v_lshlrev_b32_e32 v170, 16, v152
	v_and_b32_e32 v171, 0xffff0000, v152
	v_add_f32_e32 v168, v168, v170
	v_add_f32_e32 v169, v169, v171
	v_lshlrev_b32_e32 v170, 16, v160
	v_and_b32_e32 v171, 0xffff0000, v160
	v_add_f32_e32 v168, v168, v170
	v_add_f32_e32 v169, v169, v171
	v_lshlrev_b32_e32 v172, 16, v164
	v_and_b32_e32 v173, 0xffff0000, v164
	v_add_f32_e32 v168, v168, v172
	v_add_f32_e32 v169, v169, v173
	v_lshlrev_b32_e32 v152, 16, v153
	v_fma_f32 v168, v156, v168, -v170
	v_fma_f32 v169, v156, v169, -v171
	v_cvt_pk_bf16_f32 v148, v168, v169
	v_lshlrev_b32_e32 v168, 16, v149
	v_and_b32_e32 v169, 0xffff0000, v149
	v_and_b32_e32 v153, 0xffff0000, v153
	v_add_f32_e32 v152, v168, v152
	v_add_f32_e32 v153, v169, v153
	v_lshlrev_b32_e32 v160, 16, v161
	v_and_b32_e32 v161, 0xffff0000, v161
	v_add_f32_e32 v152, v152, v160
	v_add_f32_e32 v153, v153, v161
	v_lshlrev_b32_e32 v164, 16, v165
	v_and_b32_e32 v165, 0xffff0000, v165
	v_add_f32_e32 v152, v152, v164
	v_add_f32_e32 v153, v153, v165
	v_lshlrev_b32_e32 v164, 16, v166
	v_fma_f32 v152, v156, v152, -v160
	v_fma_f32 v153, v156, v153, -v161
	v_cvt_pk_bf16_f32 v149, v152, v153
	v_lshlrev_b32_e32 v152, 16, v150
	v_and_b32_e32 v153, 0xffff0000, v150
	v_lshlrev_b32_e32 v160, 16, v154
	v_and_b32_e32 v161, 0xffff0000, v154
	v_add_f32_e32 v152, v152, v160
	v_add_f32_e32 v153, v153, v161
	v_lshlrev_b32_e32 v160, 16, v162
	v_and_b32_e32 v161, 0xffff0000, v162
	v_add_f32_e32 v152, v152, v160
	v_add_f32_e32 v153, v153, v161
	v_and_b32_e32 v165, 0xffff0000, v166
	v_add_f32_e32 v152, v152, v164
	v_add_f32_e32 v153, v153, v165
	v_lshlrev_b32_e32 v154, 16, v155
	v_fma_f32 v152, v156, v152, -v160
	v_fma_f32 v153, v156, v153, -v161
	v_cvt_pk_bf16_f32 v150, v152, v153
	v_lshlrev_b32_e32 v152, 16, v151
	v_and_b32_e32 v153, 0xffff0000, v151
	v_and_b32_e32 v155, 0xffff0000, v155
	v_add_f32_e32 v152, v152, v154
	v_add_f32_e32 v153, v153, v155
	v_lshlrev_b32_e32 v154, 16, v163
	v_and_b32_e32 v155, 0xffff0000, v163
	v_add_f32_e32 v152, v152, v154
	v_add_f32_e32 v153, v153, v155
	v_lshlrev_b32_e32 v160, 16, v167
	v_and_b32_e32 v161, 0xffff0000, v167
	v_add_f32_e32 v152, v152, v160
	v_add_f32_e32 v153, v153, v161
	s_nop 0
	v_fma_f32 v152, v156, v152, -v154
	v_fma_f32 v153, v156, v153, -v155
	v_cvt_pk_bf16_f32 v151, v152, v153
	ds_read_b128 v[152:155], v159 offset:3360
	ds_read_b128 v[160:163], v159 offset:3888
	ds_read_b128 v[164:167], v159 offset:4416
	ds_read_b128 v[168:171], v159 offset:4944
	s_waitcnt lgkmcnt(3)
	v_lshlrev_b32_e32 v172, 16, v152
	v_and_b32_e32 v173, 0xffff0000, v152
	v_add_f32_e32 v173, 0, v173
	s_waitcnt lgkmcnt(2)
	v_lshlrev_b32_e32 v174, 16, v160
	v_and_b32_e32 v175, 0xffff0000, v160
	v_add_f32_e32 v172, v172, v174
	v_add_f32_e32 v173, v173, v175
	s_waitcnt lgkmcnt(1)
	v_lshlrev_b32_e32 v174, 16, v164
	v_and_b32_e32 v175, 0xffff0000, v164
	v_add_f32_e32 v172, v172, v174
	v_add_f32_e32 v173, v173, v175
	s_waitcnt lgkmcnt(0)
	v_lshlrev_b32_e32 v194, 16, v168
	v_and_b32_e32 v195, 0xffff0000, v168
	v_add_f32_e32 v172, v172, v194
	v_add_f32_e32 v173, v173, v195
	v_lshlrev_b32_e32 v160, 16, v161
	v_fma_f32 v172, v156, v172, -v174
	v_fma_f32 v173, v156, v173, -v175
	v_cvt_pk_bf16_f32 v152, v172, v173
	v_lshlrev_b32_e32 v172, 16, v153
	v_and_b32_e32 v173, 0xffff0000, v153
	v_and_b32_e32 v161, 0xffff0000, v161
	v_add_f32_e32 v160, v172, v160
	v_add_f32_e32 v161, v173, v161
	v_lshlrev_b32_e32 v164, 16, v165
	v_and_b32_e32 v165, 0xffff0000, v165
	v_add_f32_e32 v160, v160, v164
	v_add_f32_e32 v161, v161, v165
	v_lshlrev_b32_e32 v168, 16, v169
	v_and_b32_e32 v169, 0xffff0000, v169
	v_add_f32_e32 v160, v160, v168
	v_add_f32_e32 v161, v161, v169
	v_lshlrev_b32_e32 v168, 16, v170
	v_fma_f32 v160, v156, v160, -v164
	v_fma_f32 v161, v156, v161, -v165
	v_cvt_pk_bf16_f32 v153, v160, v161
	v_lshlrev_b32_e32 v160, 16, v154
	v_and_b32_e32 v161, 0xffff0000, v154
	v_lshlrev_b32_e32 v164, 16, v162
	v_and_b32_e32 v165, 0xffff0000, v162
	v_add_f32_e32 v160, v160, v164
	v_add_f32_e32 v161, v161, v165
	v_lshlrev_b32_e32 v164, 16, v166
	v_and_b32_e32 v165, 0xffff0000, v166
	v_add_f32_e32 v160, v160, v164
	v_add_f32_e32 v161, v161, v165
	v_and_b32_e32 v169, 0xffff0000, v170
	v_add_f32_e32 v160, v160, v168
	v_add_f32_e32 v161, v161, v169
	v_lshlrev_b32_e32 v162, 16, v163
	v_fma_f32 v160, v156, v160, -v164
	v_fma_f32 v161, v156, v161, -v165
	v_cvt_pk_bf16_f32 v154, v160, v161
	v_lshlrev_b32_e32 v160, 16, v155
	v_and_b32_e32 v161, 0xffff0000, v155
	v_and_b32_e32 v163, 0xffff0000, v163
	v_add_f32_e32 v160, v160, v162
	v_add_f32_e32 v161, v161, v163
	v_lshlrev_b32_e32 v162, 16, v167
	v_and_b32_e32 v163, 0xffff0000, v167
	v_add_f32_e32 v160, v160, v162
	v_add_f32_e32 v161, v161, v163
	v_lshlrev_b32_e32 v164, 16, v171
	v_and_b32_e32 v165, 0xffff0000, v171
	v_add_f32_e32 v160, v160, v164
	v_add_f32_e32 v161, v161, v165
	s_nop 0
	v_fma_f32 v157, v156, v161, -v163
	v_fma_f32 v156, v156, v160, -v162
.LBB0_932:
	s_andn2_saveexec_b64 s[6:7], s[6:7]
	s_cbranch_execz .LBB0_934
	v_add_u32_e32 v148, 1, v158
	v_min_u32_e32 v148, s2, v148
	v_sub_u32_e64 v149, v158, 1 clamp
	v_sub_u32_e32 v148, v148, v149
	v_cvt_f32_i32_e32 v148, v148
	v_div_scale_f32 v149, s[10:11], v148, v148, 1.0
	v_rcp_f32_e32 v150, v149
	s_nop 0
	v_fma_f32 v151, -v149, v150, 1.0
	v_fmac_f32_e32 v150, v151, v150
	v_div_scale_f32 v151, vcc, 1.0, v148, 1.0
	v_mul_f32_e32 v152, v151, v150
	v_fma_f32 v153, -v149, v152, v151
	v_fmac_f32_e32 v152, v153, v150
	v_fma_f32 v149, -v149, v152, v151
	v_div_fmas_f32 v149, v149, v150, v152
	v_div_fixup_f32 v156, v149, v148, 1.0
	ds_read_b128 v[148:151], v159 offset:3696
	ds_read_b128 v[152:155], v159 offset:4224
	s_waitcnt lgkmcnt(0)
	v_lshlrev_b32_e32 v160, 16, v148
	v_and_b32_e32 v161, 0xffff0000, v148
	v_lshlrev_b32_e32 v162, 16, v152
	v_and_b32_e32 v163, 0xffff0000, v152
	v_add_f32_e32 v160, v160, v162
	v_add_f32_e32 v161, v161, v163
	v_lshlrev_b32_e32 v152, 16, v153
	v_fma_f32 v160, v156, v160, -v162
	v_fma_f32 v161, v156, v161, -v163
	v_cvt_pk_bf16_f32 v148, v160, v161
	v_lshlrev_b32_e32 v160, 16, v149
	v_and_b32_e32 v161, 0xffff0000, v149
	v_and_b32_e32 v153, 0xffff0000, v153
	v_add_f32_e32 v160, v160, v152
	v_add_f32_e32 v161, v161, v153
	s_nop 0
	v_fma_f32 v152, v156, v160, -v152
	v_fma_f32 v153, v156, v161, -v153
	v_cvt_pk_bf16_f32 v149, v152, v153
	v_lshlrev_b32_e32 v152, 16, v150
	v_and_b32_e32 v153, 0xffff0000, v150
	v_lshlrev_b32_e32 v160, 16, v154
	v_and_b32_e32 v161, 0xffff0000, v154
	v_add_f32_e32 v152, v152, v160
	v_add_f32_e32 v153, v153, v161
	v_lshlrev_b32_e32 v154, 16, v155
	v_fma_f32 v152, v156, v152, -v160
	v_fma_f32 v153, v156, v153, -v161
	v_cvt_pk_bf16_f32 v150, v152, v153
	v_lshlrev_b32_e32 v152, 16, v151
	v_and_b32_e32 v153, 0xffff0000, v151
	v_and_b32_e32 v155, 0xffff0000, v155
	v_add_f32_e32 v152, v152, v154
	v_add_f32_e32 v153, v153, v155
	s_nop 0
	v_fma_f32 v152, v156, v152, -v154
	v_fma_f32 v153, v156, v153, -v155
	v_cvt_pk_bf16_f32 v151, v152, v153
	ds_read_b128 v[152:155], v159 offset:3760
	ds_read_b128 v[160:163], v159 offset:4288
	s_waitcnt lgkmcnt(1)
	v_lshlrev_b32_e32 v164, 16, v152
	v_and_b32_e32 v165, 0xffff0000, v152
	v_add_f32_e32 v165, 0, v165
	s_waitcnt lgkmcnt(0)
	v_lshlrev_b32_e32 v166, 16, v160
	v_and_b32_e32 v167, 0xffff0000, v160
	v_add_f32_e32 v164, v164, v166
	v_add_f32_e32 v165, v165, v167
	v_lshlrev_b32_e32 v160, 16, v161
	v_fma_f32 v164, v156, v164, -v166
	v_fma_f32 v165, v156, v165, -v167
	v_cvt_pk_bf16_f32 v152, v164, v165
	v_lshlrev_b32_e32 v164, 16, v153
	v_and_b32_e32 v165, 0xffff0000, v153
	v_and_b32_e32 v161, 0xffff0000, v161
	v_add_f32_e32 v164, v164, v160
	v_add_f32_e32 v165, v165, v161
	s_nop 0
	v_fma_f32 v160, v156, v164, -v160
	v_fma_f32 v161, v156, v165, -v161
	v_cvt_pk_bf16_f32 v153, v160, v161
	v_lshlrev_b32_e32 v160, 16, v154
	v_and_b32_e32 v161, 0xffff0000, v154
	v_lshlrev_b32_e32 v164, 16, v162
	v_and_b32_e32 v165, 0xffff0000, v162
	v_add_f32_e32 v160, v160, v164
	v_add_f32_e32 v161, v161, v165
	v_lshlrev_b32_e32 v162, 16, v163
	v_fma_f32 v160, v156, v160, -v164
	v_fma_f32 v161, v156, v161, -v165
	v_cvt_pk_bf16_f32 v154, v160, v161
	v_lshlrev_b32_e32 v160, 16, v155
	v_and_b32_e32 v161, 0xffff0000, v155
	v_and_b32_e32 v163, 0xffff0000, v163
	v_add_f32_e32 v160, v160, v162
	v_add_f32_e32 v161, v161, v163
	s_nop 0
	v_fma_f32 v157, v156, v161, -v163
	v_fma_f32 v156, v156, v160, -v162
.LBB0_934:
	s_or_b64 exec, exec, s[6:7]
	s_ashr_i32 s3, s8, 31
	v_mov_b32_e32 v161, s3
	v_or_b32_e32 v160, s8, v188
	v_lshlrev_b64 v[160:161], 11, v[160:161]
	v_lshl_add_u64 v[194:195], v[186:187], 0, v[160:161]
	v_mfma_f32_16x16x32_bf16 v[160:163], v[0:3], v[148:151], 0
	v_cvt_pk_bf16_f32 v155, v156, v157
	v_mfma_f32_16x16x32_bf16 v[164:167], v[16:19], v[148:151], 0
	s_nop 0
	v_mfma_f32_16x16x32_bf16 v[160:163], v[4:7], v[152:155], v[160:163]
	v_mfma_f32_16x16x32_bf16 v[168:171], v[24:27], v[148:151], 0
	v_mfma_f32_16x16x32_bf16 v[148:151], v[40:43], v[148:151], 0
	s_nop 5
	v_mul_f32_e64 v156, v12, v160
	v_mul_f32_e64 v157, v13, v161
	v_lshlrev_b32_e32 v160, 16, v144
	v_and_b32_e32 v161, 0xffff0000, v144
	v_mfma_f32_16x16x32_bf16 v[164:167], v[20:23], v[152:155], v[164:167]
	v_mul_f32_e64 v156, v156, v160
	v_mul_f32_e64 v157, v157, v161
	v_lshlrev_b32_e32 v160, 16, v146
	v_cvt_pk_bf16_f32 v144, v156, v157
	v_mfma_f32_16x16x32_bf16 v[168:171], v[28:31], v[152:155], v[168:171]
	v_lshlrev_b32_e32 v156, 16, v145
	v_and_b32_e32 v157, 0xffff0000, v145
	v_and_b32_e32 v161, 0xffff0000, v146
	v_mfma_f32_16x16x32_bf16 v[148:151], v[44:47], v[152:155], v[148:151]
	v_mul_f32_e64 v154, v14, v162
	v_mul_f32_e64 v155, v15, v163
	v_lshl_add_u64 v[152:153], v[194:195], 0, v[176:177]
	v_mul_f32_e32 v154, v154, v156
	v_mul_f32_e32 v155, v155, v157
	v_mul_f32_e32 v156, v8, v164
	v_mul_f32_e32 v157, v9, v165
	v_cvt_pk_bf16_f32 v145, v154, v155
	v_mul_f32_e32 v156, v156, v160
	v_mul_f32_e32 v157, v157, v161
	v_mul_f32_e32 v154, v10, v166
	v_mul_f32_e32 v155, v11, v167
	v_cvt_pk_bf16_f32 v146, v156, v157
	v_lshlrev_b32_e32 v156, 16, v147
	v_and_b32_e32 v157, 0xffff0000, v147
	v_mul_f32_e32 v154, v154, v156
	v_mul_f32_e32 v155, v155, v157
	s_nop 0
	v_cvt_pk_bf16_f32 v147, v154, v155
	global_store_dwordx4 v[152:153], v[144:147], off
	v_lshlrev_b32_e32 v154, 16, v140
	v_and_b32_e32 v155, 0xffff0000, v140
	v_mul_f32_e32 v146, v36, v168
	v_mul_f32_e32 v147, v37, v169
	v_mul_f32_e32 v144, v38, v170
	v_mul_f32_e32 v145, v39, v171
	v_mul_f32_e32 v146, v146, v154
	v_mul_f32_e32 v147, v147, v155
	s_nop 0
	v_cvt_pk_bf16_f32 v140, v146, v147
	v_lshlrev_b32_e32 v146, 16, v141
	v_and_b32_e32 v147, 0xffff0000, v141
	v_mul_f32_e32 v144, v144, v146
	v_mul_f32_e32 v145, v145, v147
	v_mul_f32_e32 v146, v32, v148
	v_mul_f32_e32 v147, v33, v149
	v_lshlrev_b32_e32 v148, 16, v142
	v_and_b32_e32 v149, 0xffff0000, v142
	v_mul_f32_e32 v146, v146, v148
	v_mul_f32_e32 v147, v147, v149
	v_cvt_pk_bf16_f32 v141, v144, v145
	v_mul_f32_e32 v144, v34, v150
	v_mul_f32_e32 v145, v35, v151
	v_cvt_pk_bf16_f32 v142, v146, v147
	v_lshlrev_b32_e32 v146, 16, v143
	v_and_b32_e32 v147, 0xffff0000, v143
	v_mul_f32_e32 v144, v144, v146
	v_mul_f32_e32 v145, v145, v147
	s_nop 0
	v_cvt_pk_bf16_f32 v143, v144, v145
	global_store_dwordx4 v[152:153], v[140:143], off offset:64
	s_and_saveexec_b64 s[6:7], s[36:37]
	s_xor_b64 s[6:7], exec, s[6:7]
	s_cbranch_execz .LBB0_936
	v_add_u32_e32 v140, 4, v158
	v_min_u32_e32 v140, s2, v140
	v_sub_u32_e64 v141, v158, 4 clamp
	v_sub_u32_e32 v140, v140, v141
	v_cvt_f32_i32_e32 v140, v140
	v_div_scale_f32 v141, s[10:11], v140, v140, 1.0
	v_rcp_f32_e32 v142, v141
	s_nop 0
	v_fma_f32 v143, -v141, v142, 1.0
	v_fmac_f32_e32 v142, v143, v142
	v_div_scale_f32 v143, vcc, 1.0, v140, 1.0
	v_mul_f32_e32 v144, v143, v142
	v_fma_f32 v145, -v141, v144, v143
	v_fmac_f32_e32 v144, v145, v142
	v_fma_f32 v141, -v141, v144, v143
	v_div_fmas_f32 v141, v141, v142, v144
	v_div_fixup_f32 v196, v141, v140, 1.0
	ds_read_b128 v[140:143], v244 offset:2112
	s_waitcnt lgkmcnt(0)
	v_lshlrev_b32_e32 v164, 16, v140
	v_and_b32_e32 v165, 0xffff0000, v140
	v_lshlrev_b32_e32 v166, 16, v141
	v_and_b32_e32 v167, 0xffff0000, v141
	v_lshlrev_b32_e32 v168, 16, v142
	v_and_b32_e32 v169, 0xffff0000, v142
	v_lshlrev_b32_e32 v170, 16, v143
	v_and_b32_e32 v171, 0xffff0000, v143
	ds_read_b128 v[140:143], v244 offset:2640
	v_add_f32_e32 v164, 0, v164
	v_add_f32_e32 v165, 0, v165
	s_waitcnt lgkmcnt(0)
	v_lshlrev_b32_e32 v172, 16, v140
	v_and_b32_e32 v173, 0xffff0000, v140
	v_lshlrev_b32_e32 v174, 16, v141
	v_and_b32_e32 v175, 0xffff0000, v141
	v_lshlrev_b32_e32 v198, 16, v142
	v_and_b32_e32 v199, 0xffff0000, v142
	v_lshlrev_b32_e32 v200, 16, v143
	v_and_b32_e32 v201, 0xffff0000, v143
	ds_read_b128 v[140:143], v244 offset:3168
	ds_read_b128 v[144:147], v244 offset:3696
	ds_read_b128 v[148:151], v244 offset:4224
	ds_read_b128 v[152:155], v244 offset:4752
	ds_read_b128 v[156:159], v244 offset:5280
	ds_read_b128 v[160:163], v244 offset:5808
	v_add_f32_e32 v164, v164, v172
	v_add_f32_e32 v165, v165, v173
	s_waitcnt lgkmcnt(5)
	v_lshlrev_b32_e32 v172, 16, v140
	v_and_b32_e32 v173, 0xffff0000, v140
	v_add_f32_e32 v164, v164, v172
	v_add_f32_e32 v165, v165, v173
	s_waitcnt lgkmcnt(4)
	v_lshlrev_b32_e32 v172, 16, v144
	v_and_b32_e32 v173, 0xffff0000, v144
	v_add_f32_e32 v164, v164, v172
	v_add_f32_e32 v165, v165, v173
	s_waitcnt lgkmcnt(3)
	v_lshlrev_b32_e32 v172, 16, v148
	v_and_b32_e32 v173, 0xffff0000, v148
	v_add_f32_e32 v164, v164, v172
	v_add_f32_e32 v165, v165, v173
	s_waitcnt lgkmcnt(2)
	v_lshlrev_b32_e32 v202, 16, v152
	v_and_b32_e32 v203, 0xffff0000, v152
	v_add_f32_e32 v164, v164, v202
	v_add_f32_e32 v165, v165, v203
	s_waitcnt lgkmcnt(1)
	v_lshlrev_b32_e32 v202, 16, v156
	v_and_b32_e32 v203, 0xffff0000, v156
	v_add_f32_e32 v164, v164, v202
	v_add_f32_e32 v165, v165, v203
	s_waitcnt lgkmcnt(0)
	v_lshlrev_b32_e32 v202, 16, v160
	v_and_b32_e32 v203, 0xffff0000, v160
	v_add_f32_e32 v164, v164, v202
	v_add_f32_e32 v165, v165, v203
	v_lshlrev_b32_e32 v144, 16, v145
	v_fma_f32 v164, v196, v164, -v172
	v_fma_f32 v165, v196, v165, -v173
	v_cvt_pk_bf16_f32 v140, v164, v165
	v_add_f32_e32 v164, 0, v166
	v_add_f32_e32 v165, 0, v167
	v_lshlrev_b32_e32 v166, 16, v141
	v_add_f32_e32 v164, v164, v174
	v_add_f32_e32 v165, v165, v175
	v_and_b32_e32 v167, 0xffff0000, v141
	v_add_f32_e32 v164, v164, v166
	v_add_f32_e32 v165, v165, v167
	v_and_b32_e32 v145, 0xffff0000, v145
	v_add_f32_e32 v144, v164, v144
	v_add_f32_e32 v145, v165, v145
	v_lshlrev_b32_e32 v148, 16, v149
	v_and_b32_e32 v149, 0xffff0000, v149
	v_add_f32_e32 v144, v144, v148
	v_add_f32_e32 v145, v145, v149
	v_lshlrev_b32_e32 v152, 16, v153
	v_and_b32_e32 v153, 0xffff0000, v153
	v_add_f32_e32 v144, v144, v152
	v_add_f32_e32 v145, v145, v153
	v_lshlrev_b32_e32 v152, 16, v157
	v_and_b32_e32 v153, 0xffff0000, v157
	v_add_f32_e32 v144, v144, v152
	v_add_f32_e32 v145, v145, v153
	v_lshlrev_b32_e32 v152, 16, v161
	v_and_b32_e32 v153, 0xffff0000, v161
	v_add_f32_e32 v144, v144, v152
	v_add_f32_e32 v145, v145, v153
	v_lshlrev_b32_e32 v152, 16, v154
	v_fma_f32 v144, v196, v144, -v148
	v_fma_f32 v145, v196, v145, -v149
	v_cvt_pk_bf16_f32 v141, v144, v145
	v_add_f32_e32 v144, 0, v168
	v_add_f32_e32 v145, 0, v169
	v_lshlrev_b32_e32 v148, 16, v142
	v_add_f32_e32 v144, v144, v198
	v_add_f32_e32 v145, v145, v199
	v_and_b32_e32 v149, 0xffff0000, v142
	v_add_f32_e32 v144, v144, v148
	v_add_f32_e32 v145, v145, v149
	v_lshlrev_b32_e32 v148, 16, v146
	v_and_b32_e32 v149, 0xffff0000, v146
	v_add_f32_e32 v144, v144, v148
	v_add_f32_e32 v145, v145, v149
	v_lshlrev_b32_e32 v148, 16, v150
	v_and_b32_e32 v149, 0xffff0000, v150
	v_add_f32_e32 v144, v144, v148
	v_add_f32_e32 v145, v145, v149
	v_and_b32_e32 v153, 0xffff0000, v154
	v_add_f32_e32 v144, v144, v152
	v_add_f32_e32 v145, v145, v153
	v_lshlrev_b32_e32 v152, 16, v158
	v_and_b32_e32 v153, 0xffff0000, v158
	v_add_f32_e32 v144, v144, v152
	v_add_f32_e32 v145, v145, v153
	v_lshlrev_b32_e32 v152, 16, v162
	v_and_b32_e32 v153, 0xffff0000, v162
	v_add_f32_e32 v144, v144, v152
	v_add_f32_e32 v145, v145, v153
	v_lshlrev_b32_e32 v146, 16, v147
	v_fma_f32 v144, v196, v144, -v148
	v_fma_f32 v145, v196, v145, -v149
	v_cvt_pk_bf16_f32 v142, v144, v145
	v_add_f32_e32 v144, 0, v170
	v_add_f32_e32 v145, 0, v171
	v_lshlrev_b32_e32 v148, 16, v143
	v_add_f32_e32 v144, v144, v200
	v_add_f32_e32 v145, v145, v201
	v_and_b32_e32 v149, 0xffff0000, v143
	v_add_f32_e32 v144, v144, v148
	v_add_f32_e32 v145, v145, v149
	v_and_b32_e32 v147, 0xffff0000, v147
	v_add_f32_e32 v144, v144, v146
	v_add_f32_e32 v145, v145, v147
	v_lshlrev_b32_e32 v146, 16, v151
	v_and_b32_e32 v147, 0xffff0000, v151
	v_add_f32_e32 v144, v144, v146
	v_add_f32_e32 v145, v145, v147
	v_lshlrev_b32_e32 v148, 16, v155
	v_and_b32_e32 v149, 0xffff0000, v155
	v_add_f32_e32 v144, v144, v148
	v_add_f32_e32 v145, v145, v149
	v_lshlrev_b32_e32 v148, 16, v159
	v_and_b32_e32 v149, 0xffff0000, v159
	v_add_f32_e32 v144, v144, v148
	v_add_f32_e32 v145, v145, v149
	v_lshlrev_b32_e32 v148, 16, v163
	v_and_b32_e32 v149, 0xffff0000, v163
	v_add_f32_e32 v144, v144, v148
	v_add_f32_e32 v145, v145, v149
	s_nop 0
	v_fma_f32 v144, v196, v144, -v146
	v_fma_f32 v145, v196, v145, -v147
	v_cvt_pk_bf16_f32 v143, v144, v145
	ds_read_b128 v[144:147], v244 offset:2176
	ds_read_b128 v[148:151], v244 offset:2704
	ds_read_b128 v[152:155], v244 offset:3232
	ds_read_b128 v[156:159], v244 offset:3760
	ds_read_b128 v[160:163], v244 offset:4288
	s_waitcnt lgkmcnt(4)
	v_lshlrev_b32_e32 v164, 16, v144
	v_and_b32_e32 v165, 0xffff0000, v144
	v_lshlrev_b32_e32 v144, 16, v145
	v_and_b32_e32 v145, 0xffff0000, v145
	v_add_f32_e32 v165, 0, v165
	s_waitcnt lgkmcnt(3)
	v_lshlrev_b32_e32 v166, 16, v148
	v_and_b32_e32 v167, 0xffff0000, v148
	v_lshlrev_b32_e32 v148, 16, v149
	v_and_b32_e32 v149, 0xffff0000, v149
	v_add_f32_e32 v164, v164, v166
	v_add_f32_e32 v165, v165, v167
	s_waitcnt lgkmcnt(2)
	v_lshlrev_b32_e32 v166, 16, v152
	v_and_b32_e32 v167, 0xffff0000, v152
	v_add_f32_e32 v144, v144, v148
	v_add_f32_e32 v145, v145, v149
	v_lshlrev_b32_e32 v148, 16, v153
	v_and_b32_e32 v149, 0xffff0000, v153
	v_lshlrev_b32_e32 v152, 16, v146
	v_and_b32_e32 v153, 0xffff0000, v146
	v_lshlrev_b32_e32 v146, 16, v147
	v_and_b32_e32 v147, 0xffff0000, v147
	v_add_f32_e32 v164, v164, v166
	v_add_f32_e32 v165, v165, v167
	s_waitcnt lgkmcnt(1)
	v_lshlrev_b32_e32 v166, 16, v156
	v_and_b32_e32 v167, 0xffff0000, v156
	v_add_f32_e32 v144, v144, v148
	v_add_f32_e32 v145, v145, v149
	v_lshlrev_b32_e32 v148, 16, v157
	v_and_b32_e32 v149, 0xffff0000, v157
	v_lshlrev_b32_e32 v156, 16, v150
	v_and_b32_e32 v157, 0xffff0000, v150
	v_lshlrev_b32_e32 v150, 16, v151
	v_and_b32_e32 v151, 0xffff0000, v151
	v_add_f32_e32 v152, v152, v156
	v_add_f32_e32 v153, v153, v157
	v_lshlrev_b32_e32 v156, 16, v154
	v_and_b32_e32 v157, 0xffff0000, v154
	v_add_f32_e32 v146, v146, v150
	v_add_f32_e32 v147, v147, v151
	v_lshlrev_b32_e32 v150, 16, v155
	v_and_b32_e32 v151, 0xffff0000, v155
	v_add_f32_e32 v152, v152, v156
	v_add_f32_e32 v153, v153, v157
	v_lshlrev_b32_e32 v156, 16, v158
	v_and_b32_e32 v157, 0xffff0000, v158
	v_add_f32_e32 v146, v146, v150
	v_add_f32_e32 v147, v147, v151
	v_lshlrev_b32_e32 v150, 16, v159
	v_and_b32_e32 v151, 0xffff0000, v159
	v_add_f32_e32 v164, v164, v166
	v_add_f32_e32 v165, v165, v167
	s_waitcnt lgkmcnt(0)
	v_lshlrev_b32_e32 v206, 16, v160
	v_and_b32_e32 v207, 0xffff0000, v160
	v_add_f32_e32 v148, v144, v148
	v_add_f32_e32 v149, v145, v149
	v_lshlrev_b32_e32 v144, 16, v161
	v_and_b32_e32 v145, 0xffff0000, v161
	v_add_f32_e32 v156, v152, v156
	v_add_f32_e32 v157, v153, v157
	v_lshlrev_b32_e32 v152, 16, v162
	v_and_b32_e32 v153, 0xffff0000, v162
	v_add_f32_e32 v150, v146, v150
	v_add_f32_e32 v151, v147, v151
	v_lshlrev_b32_e32 v146, 16, v163
	v_and_b32_e32 v147, 0xffff0000, v163
	v_add_f32_e32 v222, v164, v206
	v_add_f32_e32 v223, v165, v207
	v_add_f32_e32 v148, v148, v144
	v_add_f32_e32 v149, v149, v145
	v_add_f32_e32 v156, v156, v152
	v_add_f32_e32 v157, v157, v153
	v_add_f32_e32 v150, v150, v146
	v_add_f32_e32 v151, v151, v147
.LBB0_936:
	s_or_saveexec_b64 s[6:7], s[6:7]
	v_mov_b32_e32 v154, v245
	v_mov_b32_e32 v155, v246
	v_mov_b32_e32 v159, v247
	s_xor_b64 exec, exec, s[6:7]
	s_cbranch_execz .LBB0_919
	v_add_u32_e32 v140, 8, v158
	v_min_u32_e32 v140, s2, v140
	v_sub_u32_e64 v141, v158, 8 clamp
	v_sub_u32_e32 v140, v140, v141
	v_cvt_f32_i32_e32 v140, v140
	v_div_scale_f32 v141, s[2:3], v140, v140, 1.0
	v_rcp_f32_e32 v142, v141
	s_nop 0
	v_fma_f32 v143, -v141, v142, 1.0
	v_fmac_f32_e32 v142, v143, v142
	v_div_scale_f32 v143, vcc, 1.0, v140, 1.0
	v_mul_f32_e32 v144, v143, v142
	v_fma_f32 v145, -v141, v144, v143
	v_fmac_f32_e32 v144, v145, v142
	v_fma_f32 v141, -v141, v144, v143
	v_div_fmas_f32 v141, v141, v142, v144
	v_div_fixup_f32 v196, v141, v140, 1.0
	ds_read_b128 v[140:143], v244
	ds_read_b128 v[144:147], v244 offset:528
	ds_read_b128 v[148:151], v244 offset:1056
	ds_read_b128 v[152:155], v244 offset:1584
	ds_read_b128 v[156:159], v244 offset:2112
	ds_read_b128 v[160:163], v244 offset:2640
	ds_read_b128 v[164:167], v244 offset:3168
	s_waitcnt lgkmcnt(0)
	v_lshlrev_b32_e32 v168, 16, v140
	v_and_b32_e32 v169, 0xffff0000, v140
	v_lshlrev_b32_e32 v140, 16, v141
	v_and_b32_e32 v141, 0xffff0000, v141
	v_lshlrev_b32_e32 v170, 16, v144
	v_and_b32_e32 v171, 0xffff0000, v144
	v_lshlrev_b32_e32 v144, 16, v145
	v_and_b32_e32 v145, 0xffff0000, v145
	v_add_f32_e32 v140, v140, v144
	v_add_f32_e32 v141, v141, v145
	v_lshlrev_b32_e32 v144, 16, v149
	v_and_b32_e32 v145, 0xffff0000, v149
	v_add_f32_e32 v168, v168, v170
	v_add_f32_e32 v169, v169, v171
	v_lshlrev_b32_e32 v170, 16, v148
	v_and_b32_e32 v171, 0xffff0000, v148
	v_add_f32_e32 v140, v140, v144
	v_add_f32_e32 v141, v141, v145
	v_lshlrev_b32_e32 v144, 16, v153
	v_and_b32_e32 v145, 0xffff0000, v153
	v_add_f32_e32 v168, v168, v170
	v_add_f32_e32 v169, v169, v171
	v_lshlrev_b32_e32 v170, 16, v152
	v_and_b32_e32 v171, 0xffff0000, v152
	v_add_f32_e32 v140, v140, v144
	v_add_f32_e32 v141, v141, v145
	v_lshlrev_b32_e32 v144, 16, v157
	v_and_b32_e32 v145, 0xffff0000, v157
	v_add_f32_e32 v168, v168, v170
	v_add_f32_e32 v169, v169, v171
	v_lshlrev_b32_e32 v170, 16, v156
	v_and_b32_e32 v171, 0xffff0000, v156
	v_add_f32_e32 v140, v140, v144
	v_add_f32_e32 v141, v141, v145
	v_lshlrev_b32_e32 v144, 16, v161
	v_and_b32_e32 v145, 0xffff0000, v161
	v_add_f32_e32 v168, v168, v170
	v_add_f32_e32 v169, v169, v171
	v_lshlrev_b32_e32 v170, 16, v160
	v_and_b32_e32 v171, 0xffff0000, v160
	v_add_f32_e32 v140, v140, v144
	v_add_f32_e32 v141, v141, v145
	v_lshlrev_b32_e32 v144, 16, v165
	v_and_b32_e32 v145, 0xffff0000, v165
	v_add_f32_e32 v168, v168, v170
	v_add_f32_e32 v169, v169, v171
	v_lshlrev_b32_e32 v170, 16, v164
	v_and_b32_e32 v171, 0xffff0000, v164
	v_add_f32_e32 v164, v140, v144
	v_add_f32_e32 v165, v141, v145
	v_lshlrev_b32_e32 v140, 16, v142
	v_and_b32_e32 v141, 0xffff0000, v142
	v_lshlrev_b32_e32 v144, 16, v146
	v_and_b32_e32 v145, 0xffff0000, v146
	v_add_f32_e32 v140, v140, v144
	v_add_f32_e32 v141, v141, v145
	v_lshlrev_b32_e32 v144, 16, v150
	v_and_b32_e32 v145, 0xffff0000, v150
	v_add_f32_e32 v140, v140, v144
	v_add_f32_e32 v141, v141, v145
	v_lshlrev_b32_e32 v144, 16, v154
	v_and_b32_e32 v145, 0xffff0000, v154
	v_add_f32_e32 v140, v140, v144
	v_add_f32_e32 v141, v141, v145
	v_lshlrev_b32_e32 v144, 16, v158
	v_and_b32_e32 v145, 0xffff0000, v158
	v_add_f32_e32 v140, v140, v144
	v_add_f32_e32 v141, v141, v145
	v_lshlrev_b32_e32 v144, 16, v162
	v_and_b32_e32 v145, 0xffff0000, v162
	v_add_f32_e32 v140, v140, v144
	v_add_f32_e32 v141, v141, v145
	v_lshlrev_b32_e32 v144, 16, v166
	v_and_b32_e32 v145, 0xffff0000, v166
	v_add_f32_e32 v168, v168, v170
	v_add_f32_e32 v169, v169, v171
	v_add_f32_e32 v170, v140, v144
	v_add_f32_e32 v171, v141, v145
	v_lshlrev_b32_e32 v140, 16, v143
	v_and_b32_e32 v141, 0xffff0000, v143
	v_lshlrev_b32_e32 v142, 16, v147
	v_and_b32_e32 v143, 0xffff0000, v147
	v_add_f32_e32 v140, v140, v142
	v_add_f32_e32 v141, v141, v143
	v_lshlrev_b32_e32 v142, 16, v151
	v_and_b32_e32 v143, 0xffff0000, v151
	v_add_f32_e32 v140, v140, v142
	v_add_f32_e32 v141, v141, v143
	v_lshlrev_b32_e32 v142, 16, v155
	v_and_b32_e32 v143, 0xffff0000, v155
	v_add_f32_e32 v140, v140, v142
	v_add_f32_e32 v141, v141, v143
	v_lshlrev_b32_e32 v142, 16, v159
	v_and_b32_e32 v143, 0xffff0000, v159
	v_add_f32_e32 v140, v140, v142
	v_add_f32_e32 v141, v141, v143
	v_lshlrev_b32_e32 v142, 16, v163
	v_and_b32_e32 v143, 0xffff0000, v163
	v_add_f32_e32 v140, v140, v142
	v_add_f32_e32 v141, v141, v143
	v_lshlrev_b32_e32 v142, 16, v167
	v_and_b32_e32 v143, 0xffff0000, v167
	v_add_f32_e32 v166, v140, v142
	v_add_f32_e32 v167, v141, v143
	ds_read_b128 v[140:143], v244 offset:3696
	s_waitcnt lgkmcnt(0)
	v_lshlrev_b32_e32 v172, 16, v140
	v_and_b32_e32 v173, 0xffff0000, v140
	v_lshlrev_b32_e32 v174, 16, v141
	v_and_b32_e32 v175, 0xffff0000, v141
	v_lshlrev_b32_e32 v198, 16, v142
	v_and_b32_e32 v199, 0xffff0000, v142
	v_lshlrev_b32_e32 v200, 16, v143
	v_and_b32_e32 v201, 0xffff0000, v143
	ds_read_b128 v[140:143], v244 offset:4224
	v_add_f32_e32 v168, v168, v172
	v_add_f32_e32 v169, v169, v173
	v_add_f32_e32 v164, v164, v174
	v_add_f32_e32 v165, v165, v175
	s_waitcnt lgkmcnt(0)
	v_lshlrev_b32_e32 v202, 16, v140
	v_and_b32_e32 v203, 0xffff0000, v140
	v_lshlrev_b32_e32 v204, 16, v141
	v_and_b32_e32 v205, 0xffff0000, v141
	v_lshlrev_b32_e32 v206, 16, v142
	v_and_b32_e32 v207, 0xffff0000, v142
	v_lshlrev_b32_e32 v208, 16, v143
	v_and_b32_e32 v209, 0xffff0000, v143
	ds_read_b128 v[140:143], v244 offset:4752
	v_add_f32_e32 v168, v168, v202
	v_add_f32_e32 v169, v169, v203
	v_add_f32_e32 v164, v164, v204
	v_add_f32_e32 v165, v165, v205
	s_waitcnt lgkmcnt(0)
	v_lshlrev_b32_e32 v210, 16, v140
	v_and_b32_e32 v211, 0xffff0000, v140
	v_lshlrev_b32_e32 v212, 16, v141
	v_and_b32_e32 v213, 0xffff0000, v141
	v_lshlrev_b32_e32 v214, 16, v142
	v_and_b32_e32 v215, 0xffff0000, v142
	v_lshlrev_b32_e32 v216, 16, v143
	v_and_b32_e32 v217, 0xffff0000, v143
	ds_read_b128 v[140:143], v244 offset:5280
	ds_read_b128 v[144:147], v244 offset:5808
	ds_read_b128 v[148:151], v244 offset:6336
	ds_read_b128 v[152:155], v244 offset:6864
	ds_read_b128 v[156:159], v244 offset:7392
	ds_read_b128 v[160:163], v244 offset:7920
	v_add_f32_e32 v168, v168, v210
	v_add_f32_e32 v169, v169, v211
	s_waitcnt lgkmcnt(5)
	v_lshlrev_b32_e32 v172, 16, v140
	v_and_b32_e32 v173, 0xffff0000, v140
	v_add_f32_e32 v168, v168, v172
	v_add_f32_e32 v169, v169, v173
	s_waitcnt lgkmcnt(4)
	v_lshlrev_b32_e32 v172, 16, v144
	v_and_b32_e32 v173, 0xffff0000, v144
	v_add_f32_e32 v168, v168, v172
	v_add_f32_e32 v169, v169, v173
	s_waitcnt lgkmcnt(3)
	v_lshlrev_b32_e32 v172, 16, v148
	v_and_b32_e32 v173, 0xffff0000, v148
	v_add_f32_e32 v168, v168, v172
	v_add_f32_e32 v169, v169, v173
	s_waitcnt lgkmcnt(2)
	v_lshlrev_b32_e32 v172, 16, v152
	v_and_b32_e32 v173, 0xffff0000, v152
	v_add_f32_e32 v168, v168, v172
	v_add_f32_e32 v169, v169, v173
	s_waitcnt lgkmcnt(1)
	v_lshlrev_b32_e32 v172, 16, v156
	v_and_b32_e32 v173, 0xffff0000, v156
	v_add_f32_e32 v168, v168, v172
	v_add_f32_e32 v169, v169, v173
	s_waitcnt lgkmcnt(0)
	v_lshlrev_b32_e32 v172, 16, v160
	v_and_b32_e32 v173, 0xffff0000, v160
	v_add_f32_e32 v168, v168, v172
	v_add_f32_e32 v169, v169, v173
	v_add_f32_e32 v164, v164, v212
	v_add_f32_e32 v165, v165, v213
	v_fma_f32 v168, v196, v168, -v202
	v_fma_f32 v169, v196, v169, -v203
	v_cvt_pk_bf16_f32 v140, v168, v169
	v_lshlrev_b32_e32 v168, 16, v141
	v_and_b32_e32 v169, 0xffff0000, v141
	v_add_f32_e32 v164, v164, v168
	v_add_f32_e32 v165, v165, v169
	v_lshlrev_b32_e32 v144, 16, v145
	v_and_b32_e32 v145, 0xffff0000, v145
	v_add_f32_e32 v144, v164, v144
	v_add_f32_e32 v145, v165, v145
	v_lshlrev_b32_e32 v148, 16, v149
	v_and_b32_e32 v149, 0xffff0000, v149
	v_add_f32_e32 v144, v144, v148
	v_add_f32_e32 v145, v145, v149
	v_lshlrev_b32_e32 v148, 16, v153
	v_and_b32_e32 v149, 0xffff0000, v153
	v_add_f32_e32 v144, v144, v148
	v_add_f32_e32 v145, v145, v149
	v_lshlrev_b32_e32 v148, 16, v157
	v_and_b32_e32 v149, 0xffff0000, v157
	v_add_f32_e32 v144, v144, v148
	v_add_f32_e32 v145, v145, v149
	v_lshlrev_b32_e32 v148, 16, v161
	v_and_b32_e32 v149, 0xffff0000, v161
	v_add_f32_e32 v144, v144, v148
	v_add_f32_e32 v145, v145, v149
	v_lshlrev_b32_e32 v148, 16, v142
	v_fma_f32 v144, v196, v144, -v204
	v_fma_f32 v145, v196, v145, -v205
	v_cvt_pk_bf16_f32 v141, v144, v145
	v_add_f32_e32 v144, v170, v198
	v_add_f32_e32 v145, v171, v199
	v_and_b32_e32 v149, 0xffff0000, v142
	v_add_f32_e32 v144, v144, v206
	v_add_f32_e32 v145, v145, v207
	s_nop 0
	v_add_f32_e32 v144, v144, v214
	v_add_f32_e32 v145, v145, v215
	s_nop 0
	v_add_f32_e32 v144, v144, v148
	v_add_f32_e32 v145, v145, v149
	v_lshlrev_b32_e32 v148, 16, v146
	v_and_b32_e32 v149, 0xffff0000, v146
	v_add_f32_e32 v144, v144, v148
	v_add_f32_e32 v145, v145, v149
	v_lshlrev_b32_e32 v148, 16, v150
	v_and_b32_e32 v149, 0xffff0000, v150
	v_add_f32_e32 v144, v144, v148
	v_add_f32_e32 v145, v145, v149
	v_lshlrev_b32_e32 v148, 16, v154
	v_and_b32_e32 v149, 0xffff0000, v154
	v_add_f32_e32 v144, v144, v148
	v_add_f32_e32 v145, v145, v149
	v_lshlrev_b32_e32 v148, 16, v158
	v_and_b32_e32 v149, 0xffff0000, v158
	v_add_f32_e32 v144, v144, v148
	v_add_f32_e32 v145, v145, v149
	v_lshlrev_b32_e32 v148, 16, v162
	v_and_b32_e32 v149, 0xffff0000, v162
	v_add_f32_e32 v144, v144, v148
	v_add_f32_e32 v145, v145, v149
	v_lshlrev_b32_e32 v148, 16, v143
	v_fma_f32 v144, v196, v144, -v206
	v_fma_f32 v145, v196, v145, -v207
	v_cvt_pk_bf16_f32 v142, v144, v145
	v_add_f32_e32 v144, v166, v200
	v_add_f32_e32 v145, v167, v201
	v_and_b32_e32 v149, 0xffff0000, v143
	v_add_f32_e32 v144, v144, v208
	v_add_f32_e32 v145, v145, v209
	v_lshlrev_b32_e32 v146, 16, v147
	v_add_f32_e32 v144, v144, v216
	v_add_f32_e32 v145, v145, v217
	v_and_b32_e32 v147, 0xffff0000, v147
	v_add_f32_e32 v144, v144, v148
	v_add_f32_e32 v145, v145, v149
	s_nop 0
	v_add_f32_e32 v144, v144, v146
	v_add_f32_e32 v145, v145, v147
	v_lshlrev_b32_e32 v146, 16, v151
	v_and_b32_e32 v147, 0xffff0000, v151
	v_add_f32_e32 v144, v144, v146
	v_add_f32_e32 v145, v145, v147
	v_lshlrev_b32_e32 v146, 16, v155
	v_and_b32_e32 v147, 0xffff0000, v155
	v_add_f32_e32 v144, v144, v146
	v_add_f32_e32 v145, v145, v147
	v_lshlrev_b32_e32 v146, 16, v159
	v_and_b32_e32 v147, 0xffff0000, v159
	v_add_f32_e32 v144, v144, v146
	v_add_f32_e32 v145, v145, v147
	v_lshlrev_b32_e32 v146, 16, v163
	v_and_b32_e32 v147, 0xffff0000, v163
	v_add_f32_e32 v144, v144, v146
	v_add_f32_e32 v145, v145, v147
	s_nop 0
	v_fma_f32 v144, v196, v144, -v208
	v_fma_f32 v145, v196, v145, -v209
	v_cvt_pk_bf16_f32 v143, v144, v145
	ds_read_b128 v[144:147], v244 offset:64
	ds_read_b128 v[148:151], v244 offset:592
	s_waitcnt lgkmcnt(1)
	v_lshlrev_b32_e32 v152, 16, v144
	v_and_b32_e32 v153, 0xffff0000, v144
	v_lshlrev_b32_e32 v144, 16, v145
	v_and_b32_e32 v145, 0xffff0000, v145
	s_waitcnt lgkmcnt(0)
	v_lshlrev_b32_e32 v154, 16, v148
	v_and_b32_e32 v155, 0xffff0000, v148
	v_lshlrev_b32_e32 v148, 16, v149
	v_and_b32_e32 v149, 0xffff0000, v149
	v_add_f32_e32 v202, v144, v148
	v_add_f32_e32 v203, v145, v149
	v_lshlrev_b32_e32 v144, 16, v146
	v_and_b32_e32 v145, 0xffff0000, v146
	v_lshlrev_b32_e32 v148, 16, v150
	v_and_b32_e32 v149, 0xffff0000, v150
	v_add_f32_e32 v200, v144, v148
	v_add_f32_e32 v201, v145, v149
	v_lshlrev_b32_e32 v144, 16, v147
	v_and_b32_e32 v145, 0xffff0000, v147
	v_lshlrev_b32_e32 v146, 16, v151
	v_and_b32_e32 v147, 0xffff0000, v151
	v_add_f32_e32 v198, v144, v146
	v_add_f32_e32 v199, v145, v147
	ds_read_b128 v[144:147], v244 offset:1120
	v_add_f32_e32 v152, 0, v152
	v_add_f32_e32 v153, 0, v153
	s_waitcnt lgkmcnt(0)
	v_lshlrev_b32_e32 v222, 16, v144
	v_and_b32_e32 v223, 0xffff0000, v144
	v_lshlrev_b32_e32 v216, 16, v145
	v_and_b32_e32 v217, 0xffff0000, v145
	v_lshlrev_b32_e32 v210, 16, v146
	v_and_b32_e32 v211, 0xffff0000, v146
	v_lshlrev_b32_e32 v204, 16, v147
	v_and_b32_e32 v205, 0xffff0000, v147
	ds_read_b128 v[144:147], v244 offset:1648
	v_add_f32_e32 v206, v152, v154
	v_add_f32_e32 v207, v153, v155
	v_add_f32_e32 v202, v202, v216
	v_add_f32_e32 v203, v203, v217
	v_add_f32_e32 v206, v206, v222
	v_add_f32_e32 v207, v207, v223
	s_waitcnt lgkmcnt(0)
	v_lshlrev_b32_e32 v226, 16, v144
	v_and_b32_e32 v227, 0xffff0000, v144
	v_lshlrev_b32_e32 v220, 16, v145
	v_and_b32_e32 v221, 0xffff0000, v145
	v_lshlrev_b32_e32 v214, 16, v146
	v_and_b32_e32 v215, 0xffff0000, v146
	v_lshlrev_b32_e32 v208, 16, v147
	v_and_b32_e32 v209, 0xffff0000, v147
	ds_read_b128 v[144:147], v244 offset:2176
	v_add_f32_e32 v206, v206, v226
	v_add_f32_e32 v207, v207, v227
	v_add_f32_e32 v202, v202, v220
	v_add_f32_e32 v203, v203, v221
	s_waitcnt lgkmcnt(0)
	v_lshlrev_b32_e32 v228, 16, v144
	v_and_b32_e32 v229, 0xffff0000, v144
	v_lshlrev_b32_e32 v224, 16, v145
	v_and_b32_e32 v225, 0xffff0000, v145
	v_lshlrev_b32_e32 v218, 16, v146
	v_and_b32_e32 v219, 0xffff0000, v146
	v_lshlrev_b32_e32 v212, 16, v147
	v_and_b32_e32 v213, 0xffff0000, v147
	ds_read_b128 v[144:147], v244 offset:2704
	ds_read_b128 v[148:151], v244 offset:3232
	ds_read_b128 v[152:155], v244 offset:3760
	ds_read_b128 v[156:159], v244 offset:4288
	ds_read_b128 v[160:163], v244 offset:4816
	ds_read_b128 v[164:167], v244 offset:5344
	ds_read_b128 v[168:171], v244 offset:5872
	ds_read_b128 v[172:175], v244 offset:6400
	v_add_f32_e32 v206, v206, v228
	v_add_f32_e32 v207, v207, v229
	s_waitcnt lgkmcnt(7)
	v_lshlrev_b32_e32 v222, 16, v144
	v_and_b32_e32 v223, 0xffff0000, v144
	v_add_f32_e32 v202, v202, v224
	v_add_f32_e32 v203, v203, v225
	v_lshlrev_b32_e32 v144, 16, v145
	v_and_b32_e32 v145, 0xffff0000, v145
	v_add_f32_e32 v206, v206, v222
	v_add_f32_e32 v207, v207, v223
	s_waitcnt lgkmcnt(6)
	v_lshlrev_b32_e32 v222, 16, v148
	v_and_b32_e32 v223, 0xffff0000, v148
	v_add_f32_e32 v144, v202, v144
	v_add_f32_e32 v145, v203, v145
	v_lshlrev_b32_e32 v148, 16, v149
	v_and_b32_e32 v149, 0xffff0000, v149
	v_add_f32_e32 v144, v144, v148
	v_add_f32_e32 v145, v145, v149
	s_waitcnt lgkmcnt(5)
	v_lshlrev_b32_e32 v148, 16, v153
	v_and_b32_e32 v149, 0xffff0000, v153
	v_add_f32_e32 v148, v144, v148
	v_add_f32_e32 v149, v145, v149
	s_waitcnt lgkmcnt(4)
	v_lshlrev_b32_e32 v144, 16, v157
	v_and_b32_e32 v145, 0xffff0000, v157
	v_add_f32_e32 v206, v206, v222
	v_add_f32_e32 v207, v207, v223
	v_lshlrev_b32_e32 v222, 16, v152
	v_and_b32_e32 v223, 0xffff0000, v152
	v_add_f32_e32 v148, v148, v144
	v_add_f32_e32 v149, v149, v145
	s_waitcnt lgkmcnt(3)
	v_lshlrev_b32_e32 v152, 16, v161
	v_and_b32_e32 v153, 0xffff0000, v161
	v_add_f32_e32 v148, v148, v152
	v_add_f32_e32 v149, v149, v153
	s_waitcnt lgkmcnt(2)
	v_lshlrev_b32_e32 v152, 16, v165
	v_and_b32_e32 v153, 0xffff0000, v165
	v_add_f32_e32 v148, v148, v152
	v_add_f32_e32 v149, v149, v153
	s_waitcnt lgkmcnt(1)
	v_lshlrev_b32_e32 v152, 16, v169
	v_and_b32_e32 v153, 0xffff0000, v169
	v_add_f32_e32 v148, v148, v152
	v_add_f32_e32 v149, v149, v153
	s_waitcnt lgkmcnt(0)
	v_lshlrev_b32_e32 v152, 16, v173
	v_and_b32_e32 v153, 0xffff0000, v173
	v_add_f32_e32 v148, v148, v152
	v_add_f32_e32 v149, v149, v153
	v_add_f32_e32 v152, v200, v210
	v_add_f32_e32 v153, v201, v211
	v_add_f32_e32 v222, v206, v222
	v_add_f32_e32 v223, v207, v223
	v_add_f32_e32 v152, v152, v214
	v_add_f32_e32 v153, v153, v215
	v_lshlrev_b32_e32 v206, 16, v156
	v_and_b32_e32 v207, 0xffff0000, v156
	v_add_f32_e32 v152, v152, v218
	v_add_f32_e32 v153, v153, v219
	v_lshlrev_b32_e32 v156, 16, v146
	v_and_b32_e32 v157, 0xffff0000, v146
	v_add_f32_e32 v152, v152, v156
	v_add_f32_e32 v153, v153, v157
	v_lshlrev_b32_e32 v156, 16, v150
	v_and_b32_e32 v157, 0xffff0000, v150
	v_add_f32_e32 v152, v152, v156
	v_add_f32_e32 v153, v153, v157
	v_lshlrev_b32_e32 v156, 16, v154
	v_and_b32_e32 v157, 0xffff0000, v154
	v_add_f32_e32 v156, v152, v156
	v_add_f32_e32 v157, v153, v157
	v_lshlrev_b32_e32 v152, 16, v158
	v_and_b32_e32 v153, 0xffff0000, v158
	v_lshlrev_b32_e32 v226, 16, v160
	v_and_b32_e32 v227, 0xffff0000, v160
	v_add_f32_e32 v156, v156, v152
	v_add_f32_e32 v157, v157, v153
	v_lshlrev_b32_e32 v160, 16, v162
	v_and_b32_e32 v161, 0xffff0000, v162
	v_add_f32_e32 v156, v156, v160
	v_add_f32_e32 v157, v157, v161
	v_lshlrev_b32_e32 v160, 16, v166
	v_and_b32_e32 v161, 0xffff0000, v166
	v_add_f32_e32 v156, v156, v160
	v_add_f32_e32 v157, v157, v161
	v_lshlrev_b32_e32 v160, 16, v170
	v_and_b32_e32 v161, 0xffff0000, v170
	v_add_f32_e32 v156, v156, v160
	v_add_f32_e32 v157, v157, v161
	v_lshlrev_b32_e32 v160, 16, v174
	v_and_b32_e32 v161, 0xffff0000, v174
	v_add_f32_e32 v156, v156, v160
	v_add_f32_e32 v157, v157, v161
	v_add_f32_e32 v160, v198, v204
	v_add_f32_e32 v161, v199, v205
	v_lshlrev_b32_e32 v146, 16, v147
	v_add_f32_e32 v160, v160, v208
	v_add_f32_e32 v161, v161, v209
	v_and_b32_e32 v147, 0xffff0000, v147
	v_add_f32_e32 v160, v160, v212
	v_add_f32_e32 v161, v161, v213
	v_lshlrev_b32_e32 v150, 16, v151
	v_add_f32_e32 v146, v160, v146
	v_add_f32_e32 v147, v161, v147
	v_and_b32_e32 v151, 0xffff0000, v151
	v_add_f32_e32 v146, v146, v150
	v_add_f32_e32 v147, v147, v151
	v_lshlrev_b32_e32 v150, 16, v155
	v_and_b32_e32 v151, 0xffff0000, v155
	v_add_f32_e32 v150, v146, v150
	v_add_f32_e32 v151, v147, v151
	v_lshlrev_b32_e32 v146, 16, v159
	v_and_b32_e32 v147, 0xffff0000, v159
	v_add_f32_e32 v222, v222, v206
	v_add_f32_e32 v223, v223, v207
	v_add_f32_e32 v150, v150, v146
	v_add_f32_e32 v151, v151, v147
	v_lshlrev_b32_e32 v154, 16, v163
	v_and_b32_e32 v155, 0xffff0000, v163
	v_add_f32_e32 v222, v222, v226
	v_add_f32_e32 v223, v223, v227
	v_lshlrev_b32_e32 v226, 16, v164
	v_and_b32_e32 v227, 0xffff0000, v164
	v_add_f32_e32 v150, v150, v154
	v_add_f32_e32 v151, v151, v155
	v_lshlrev_b32_e32 v154, 16, v167
	v_and_b32_e32 v155, 0xffff0000, v167
	v_add_f32_e32 v222, v222, v226
	v_add_f32_e32 v223, v223, v227
	v_lshlrev_b32_e32 v226, 16, v168
	v_and_b32_e32 v227, 0xffff0000, v168
	v_add_f32_e32 v150, v150, v154
	v_add_f32_e32 v151, v151, v155
	v_lshlrev_b32_e32 v154, 16, v171
	v_and_b32_e32 v155, 0xffff0000, v171
	v_add_f32_e32 v222, v222, v226
	v_add_f32_e32 v223, v223, v227
	v_lshlrev_b32_e32 v226, 16, v172
	v_and_b32_e32 v227, 0xffff0000, v172
	v_add_f32_e32 v150, v150, v154
	v_add_f32_e32 v151, v151, v155
	v_lshlrev_b32_e32 v154, 16, v175
	v_and_b32_e32 v155, 0xffff0000, v175
	v_add_f32_e32 v222, v222, v226
	v_add_f32_e32 v223, v223, v227
	v_add_f32_e32 v150, v150, v154
	v_add_f32_e32 v151, v151, v155
	v_mov_b32_e32 v154, v248
	v_mov_b32_e32 v155, v249
	v_mov_b32_e32 v159, v233
	s_branch .LBB0_919
